# PH5: the first finisher of each attention pair takes that unit's long-conv item directly (exactly one conv item per workgroup, no dequeue); the queue serves only the short items
# speedup vs baseline: 1.0136x; 1.0025x over previous
.LBB0_1840:
	s_and_saveexec_b64 s[4:5], s[2:3]
	s_cbranch_execz .LBB0_1844
	s_mov_b64 s[10:11], exec
	v_mbcnt_lo_u32_b32 v0, s10, 0
	v_mbcnt_hi_u32_b32 v0, s11, v0
	v_cmp_eq_u32_e32 vcc, 0, v0
	s_and_saveexec_b64 s[6:7], vcc
	s_cbranch_execz .LBB0_1843
	s_cmp_eq_u32 s99, 0
	s_cbranch_scc1 .Lq_first
	s_cmp_gt_u32 s99, 1
	s_cbranch_scc1 .Lq_forced
	s_bcnt1_i32_b64 s8, s[10:11]
	v_mov_b32_e32 v1, s8
	global_atomic_add v1, v161, v1, s[36:37] offset:256 sc0
	s_branch .LBB0_1843
.Lq_forced:
	s_add_i32 s8, s99, 0xfffffe80
	v_mov_b32_e32 v1, s8
	s_branch .LBB0_1843
.Lq_first:
	v_readlane_b32 s8, v255, 2
	s_add_i32 s8, s8, 0xfffffe80
	v_mov_b32_e32 v1, s8
.LBB0_1843:
	s_or_b64 exec, exec, s[6:7]
	s_waitcnt vmcnt(0)
	v_readfirstlane_b32 s6, v1
	v_mov_b32_e32 v1, s94
	s_nop 0
	v_add_u32_e32 v0, s6, v0
	v_add_u32_e32 v0, 0x180, v0
	ds_write_b32 v1, v0

.LBB0_2228:
	s_or_b64 exec, exec, s[12:13]
	v_readlane_b32 s99, v255, 2
	s_lshr_b32 s99, s99, 1
	s_add_i32 s99, s99, 0x100
